# ff1 layer-0 GEMM k-loop: all 20 LDS fragment reads of a k-step issued up front into two register sets, counted lgkmcnt per MFMA
# speedup vs baseline: 1.0079x; 1.0032x over previous
.LBB0_1006:
	s_add_i32 s37, s35, 0x8000
	s_and_b32 s36, s37, 0x8000
	s_add_i32 s36, s36, 0
	v_add_u32_e32 v111, s36, v78
	v_lshl_add_u64 v[94:95], v[74:75], 0, s[26:27]
	v_readfirstlane_b32 s38, v111
	v_add_u32_e32 v112, 0x4000, v111
	v_lshl_add_u64 v[96:97], v[76:77], 0, s[26:27]
	v_lshl_add_u64 v[98:99], v[94:95], 0, s[10:11]
	v_add_u32_e32 v113, 0x1000, v111
	v_readfirstlane_b32 s39, v112
	s_mov_b32 m0, s38
	s_waitcnt vmcnt(0) lgkmcnt(0)
	s_barrier
	v_lshl_add_u64 v[100:101], v[96:97], 0, s[12:13]
	v_add_u32_e32 v114, 0x5000, v111
	v_readfirstlane_b32 s40, v113
	global_load_lds_dwordx4 v[98:99], off
	s_mov_b32 m0, s39
	v_lshl_add_u64 v[102:103], v[94:95], 0, s[14:15]
	v_add_u32_e32 v115, 0x2000, v111
	v_readfirstlane_b32 s41, v114
	global_load_lds_dwordx4 v[100:101], off
	s_mov_b32 m0, s40
	v_lshl_add_u64 v[104:105], v[96:97], 0, s[16:17]
	v_add_u32_e32 v116, 0x6000, v111
	v_readfirstlane_b32 s42, v115
	global_load_lds_dwordx4 v[102:103], off
	s_mov_b32 m0, s41
	v_lshl_add_u64 v[106:107], v[94:95], 0, s[18:19]
	v_add_u32_e32 v117, 0x3000, v111
	v_readfirstlane_b32 s43, v116
	global_load_lds_dwordx4 v[104:105], off
	s_mov_b32 m0, s42
	v_lshl_add_u64 v[108:109], v[96:97], 0, s[20:21]
	v_add_u32_e32 v111, 0x7000, v111
	v_readfirstlane_b32 s44, v117
	global_load_lds_dwordx4 v[106:107], off
	s_mov_b32 m0, s43
	v_lshl_add_u64 v[94:95], v[94:95], 0, s[22:23]
	v_readfirstlane_b32 s45, v111
	global_load_lds_dwordx4 v[108:109], off
	s_mov_b32 m0, s44
	v_lshl_add_u64 v[96:97], v[96:97], 0, s[24:25]
	global_load_lds_dwordx4 v[94:95], off
	s_mov_b32 m0, s45
	s_and_b32 s35, s35, 0x8000
	global_load_lds_dwordx4 v[96:97], off
	s_add_i32 s35, s35, 0
	v_add3_u32 v143, s35, v80, v81
	v_add3_u32 v145, s35, v81, v82
	v_add3_u32 v206, s35, v80, v83
	v_add3_u32 v207, s35, v82, v83
	ds_read_b128 v[102:105], v145
	ds_read_b128 v[94:97], v143 offset:16384
	ds_read_b128 v[98:101], v143 offset:18432
	ds_read_b128 v[106:109], v145 offset:2048
	ds_read_b128 v[110:113], v143 offset:20480
	ds_read_b128 v[114:117], v143 offset:22528
	ds_read_b128 v[118:121], v143 offset:24576
	ds_read_b128 v[122:125], v143 offset:26624
	ds_read_b128 v[126:129], v143 offset:28672
	ds_read_b128 v[130:133], v143 offset:30720
	ds_read_b128 v[174:177], v207
	ds_read_b128 v[166:169], v206 offset:16384
	ds_read_b128 v[170:173], v206 offset:18432
	ds_read_b128 v[178:181], v207 offset:2048
	ds_read_b128 v[182:185], v206 offset:20480
	ds_read_b128 v[186:189], v206 offset:22528
	ds_read_b128 v[190:193], v206 offset:24576
	ds_read_b128 v[194:197], v206 offset:26624
	ds_read_b128 v[198:201], v206 offset:28672
	ds_read_b128 v[202:205], v206 offset:30720
	s_add_u32 s26, s26, 0x80
	s_addc_u32 s27, s27, 0
	s_cmpk_eq_i32 s26, 0x780
	s_mov_b32 s35, s37
	s_waitcnt lgkmcnt(15)
	v_mfma_f32_16x16x32_bf16 v[60:63], v[94:97], v[102:105], v[60:63]
	v_mfma_f32_16x16x32_bf16 v[56:59], v[98:101], v[102:105], v[56:59]
	v_mfma_f32_16x16x32_bf16 v[28:31], v[94:97], v[106:109], v[28:31]
	v_mfma_f32_16x16x32_bf16 v[24:27], v[98:101], v[106:109], v[24:27]
	v_mfma_f32_16x16x32_bf16 v[52:55], v[110:113], v[102:105], v[52:55]
	v_mfma_f32_16x16x32_bf16 v[16:19], v[110:113], v[106:109], v[16:19]
	s_waitcnt lgkmcnt(14)
	v_mfma_f32_16x16x32_bf16 v[48:51], v[114:117], v[102:105], v[48:51]
	v_mfma_f32_16x16x32_bf16 v[12:15], v[114:117], v[106:109], v[12:15]
	s_waitcnt lgkmcnt(13)
	v_mfma_f32_16x16x32_bf16 v[44:47], v[118:121], v[102:105], v[44:47]
	v_mfma_f32_16x16x32_bf16 v[8:11], v[118:121], v[106:109], v[8:11]
	s_waitcnt lgkmcnt(12)
	v_mfma_f32_16x16x32_bf16 v[40:43], v[122:125], v[102:105], v[40:43]
	v_mfma_f32_16x16x32_bf16 v[4:7], v[122:125], v[106:109], v[4:7]
	s_waitcnt lgkmcnt(11)
	v_mfma_f32_16x16x32_bf16 v[36:39], v[126:129], v[102:105], v[36:39]
	v_mfma_f32_16x16x32_bf16 v[0:3], v[126:129], v[106:109], v[0:3]
	s_waitcnt lgkmcnt(10)
	v_mfma_f32_16x16x32_bf16 v[32:35], v[130:133], v[102:105], v[32:35]
	v_mfma_f32_16x16x32_bf16 v[20:23], v[130:133], v[106:109], v[20:23]
	s_waitcnt lgkmcnt(8)
	v_mfma_f32_16x16x32_bf16 v[60:63], v[166:169], v[174:177], v[60:63]
	s_waitcnt lgkmcnt(7)
	v_mfma_f32_16x16x32_bf16 v[56:59], v[170:173], v[174:177], v[56:59]
	s_waitcnt lgkmcnt(6)
	v_mfma_f32_16x16x32_bf16 v[28:31], v[166:169], v[178:181], v[28:31]
	v_mfma_f32_16x16x32_bf16 v[24:27], v[170:173], v[178:181], v[24:27]
	s_waitcnt lgkmcnt(5)
	v_mfma_f32_16x16x32_bf16 v[52:55], v[182:185], v[174:177], v[52:55]
	v_mfma_f32_16x16x32_bf16 v[16:19], v[182:185], v[178:181], v[16:19]
	s_waitcnt lgkmcnt(4)
	v_mfma_f32_16x16x32_bf16 v[48:51], v[186:189], v[174:177], v[48:51]
	v_mfma_f32_16x16x32_bf16 v[12:15], v[186:189], v[178:181], v[12:15]
	s_waitcnt lgkmcnt(3)
	v_mfma_f32_16x16x32_bf16 v[44:47], v[190:193], v[174:177], v[44:47]
	v_mfma_f32_16x16x32_bf16 v[8:11], v[190:193], v[178:181], v[8:11]
	s_waitcnt lgkmcnt(2)
	v_mfma_f32_16x16x32_bf16 v[40:43], v[194:197], v[174:177], v[40:43]
	v_mfma_f32_16x16x32_bf16 v[4:7], v[194:197], v[178:181], v[4:7]
	s_waitcnt lgkmcnt(1)
	v_mfma_f32_16x16x32_bf16 v[36:39], v[198:201], v[174:177], v[36:39]
	v_mfma_f32_16x16x32_bf16 v[0:3], v[198:201], v[178:181], v[0:3]
	s_waitcnt lgkmcnt(0)
	v_mfma_f32_16x16x32_bf16 v[32:35], v[202:205], v[174:177], v[32:35]
	v_mfma_f32_16x16x32_bf16 v[20:23], v[202:205], v[178:181], v[20:23]
	s_cbranch_scc0 .LBB0_1006
	v_add_u32_e32 v138, s36, v80
	v_add_u32_e32 v126, v138, v81
	s_waitcnt vmcnt(0)
	s_barrier
	ds_read_b128 v[74:77], v126 offset:16384
	v_add3_u32 v102, s36, v81, v82
	ds_read_b128 v[94:97], v102
	ds_read_b128 v[98:101], v126 offset:18432
	ds_read_b128 v[102:105], v102 offset:2048
	ds_read_b128 v[106:109], v126 offset:20480
	ds_read_b128 v[110:113], v126 offset:22528
	ds_read_b128 v[114:117], v126 offset:24576
	ds_read_b128 v[118:121], v126 offset:26624
	v_add3_u32 v134, s36, v83, v82
	v_add_u32_e32 v142, v138, v83
	ds_read_b128 v[122:125], v126 offset:28672
	ds_read_b128 v[126:129], v126 offset:30720
	ds_read_b128 v[130:133], v134
	ds_read_b128 v[134:137], v134 offset:2048
	ds_read_b128 v[138:141], v142 offset:16384
	ds_read_b128 v[146:149], v142 offset:18432
	s_waitcnt lgkmcnt(11)
	v_mfma_f32_16x16x32_bf16 v[56:59], v[98:101], v[94:97], v[56:59]
	s_lshl_b32 s36, s34, 7
	s_lshl_b32 s26, s33, 7
	s_ashr_i32 s27, s26, 31
	v_mfma_f32_16x16x32_bf16 v[60:63], v[74:77], v[94:97], v[60:63]
	s_lshl_b64 s[26:27], s[26:27], 1
	s_add_i32 s31, s31, s28
	s_cmpk_gt_i32 s31, 0x107f
	s_waitcnt lgkmcnt(0)
	v_mfma_f32_16x16x32_bf16 v[56:59], v[146:149], v[130:133], v[56:59]
	v_mfma_f32_16x16x32_bf16 v[48:51], v[110:113], v[94:97], v[48:51]
	v_mfma_f32_16x16x32_bf16 v[52:55], v[106:109], v[94:97], v[52:55]
	s_nop 5
	v_max_f32_e32 v56, v56, v56
	v_max_f32_e32 v57, v57, v57
	v_max_f32_e32 v56, 0, v56
	v_mfma_f32_16x16x32_bf16 v[44:47], v[114:117], v[94:97], v[44:47]
	v_max_f32_e32 v57, 0, v57
	v_max_f32_e32 v59, v59, v59
	v_max_f32_e32 v59, 0, v59
	v_mfma_f32_16x16x32_bf16 v[40:43], v[118:121], v[94:97], v[40:43]
	v_mfma_f32_16x16x32_bf16 v[36:39], v[122:125], v[94:97], v[36:39]
	v_mfma_f32_16x16x32_bf16 v[32:35], v[126:129], v[94:97], v[32:35]
	ds_read_b128 v[94:97], v142 offset:20480
	ds_read_b128 v[150:153], v142 offset:22528
	ds_read_b128 v[154:157], v142 offset:24576
	ds_read_b128 v[158:161], v142 offset:26624
	v_mfma_f32_16x16x32_bf16 v[60:63], v[138:141], v[130:133], v[60:63]
	s_waitcnt lgkmcnt(2)
	v_mfma_f32_16x16x32_bf16 v[48:51], v[150:153], v[130:133], v[48:51]
	v_mfma_f32_16x16x32_bf16 v[16:19], v[106:109], v[102:105], v[16:19]
	v_mul_f32_e64 v106, v56, v56
	v_mul_f32_e64 v107, v57, v57
	v_max_f32_e32 v57, v58, v58
	s_nop 1
	v_max_f32_e32 v60, v60, v60
	v_mfma_f32_16x16x32_bf16 v[24:27], v[98:101], v[102:105], v[24:27]
	v_add_u32_e32 v100, s36, v79
	v_mov_b64_e32 v[98:99], s[0:1]
	v_max_f32_e32 v61, v61, v61
	v_max_f32_e32 v56, v62, v62
	v_max_f32_e32 v58, 0, v57
	v_max_f32_e32 v57, v63, v63
	v_mad_i64_i32 v[100:101], s[34:35], v100, s30, v[98:99]
	v_max_f32_e32 v60, 0, v60
	v_max_f32_e32 v61, 0, v61
	v_max_f32_e32 v56, 0, v56
	v_max_f32_e32 v57, 0, v57
	v_mfma_f32_16x16x32_bf16 v[52:55], v[94:97], v[130:133], v[52:55]
	v_lshl_add_u64 v[100:101], v[100:101], 0, s[26:27]
	v_pk_mul_f32 v[60:61], v[60:61], v[60:61]
	v_pk_mul_f32 v[62:63], v[56:57], v[56:57]
	v_mfma_f32_16x16x32_bf16 v[28:31], v[74:77], v[102:105], v[28:31]
	v_max_f32_e32 v48, v48, v48
	v_max_f32_e32 v49, v49, v49
	ds_read_b128 v[74:77], v142 offset:28672
	ds_read_b128 v[162:165], v142 offset:30720
	v_mfma_f32_16x16x32_bf16 v[12:15], v[110:113], v[102:105], v[12:15]
	v_lshl_add_u64 v[100:101], v[100:101], 0, v[64:65]
	v_cvt_pk_bf16_f32 v56, v60, v61
	v_cvt_pk_bf16_f32 v57, v62, v63
	v_mfma_f32_16x16x32_bf16 v[8:11], v[114:117], v[102:105], v[8:11]
	v_max_f32_e32 v48, 0, v48
	v_max_f32_e32 v49, 0, v49
	v_max_f32_e32 v52, v52, v52
	v_mfma_f32_16x16x32_bf16 v[4:7], v[118:121], v[102:105], v[4:7]
	v_max_f32_e32 v53, v53, v53
	v_max_f32_e32 v51, v51, v51
	v_max_f32_e32 v52, 0, v52
	v_mfma_f32_16x16x32_bf16 v[0:3], v[122:125], v[102:105], v[0:3]
	v_max_f32_e32 v53, 0, v53
	v_max_f32_e32 v51, 0, v51
	v_pk_mul_f32 v[52:53], v[52:53], v[52:53]
	v_mfma_f32_16x16x32_bf16 v[20:23], v[126:129], v[102:105], v[20:23]
	v_mul_f32_e64 v102, v58, v58
	v_mul_f32_e64 v103, v59, v59
	v_cvt_pk_bf16_f32 v58, v106, v107
	v_cvt_pk_bf16_f32 v59, v102, v103
	s_waitcnt lgkmcnt(2)
	v_mfma_f32_16x16x32_bf16 v[40:43], v[158:161], v[130:133], v[40:43]
	global_store_dwordx4 v[100:101], v[56:59], off
	s_nop 1
	v_pk_mul_f32 v[56:57], v[48:49], v[48:49]
	v_max_f32_e32 v49, v50, v50
	v_max_f32_e32 v48, v54, v54
	v_max_f32_e32 v50, 0, v49
	v_max_f32_e32 v49, v55, v55
	v_mfma_f32_16x16x32_bf16 v[44:47], v[154:157], v[130:133], v[44:47]
	v_max_f32_e32 v48, 0, v48
	v_max_f32_e32 v49, 0, v49
	v_pk_mul_f32 v[54:55], v[48:49], v[48:49]
	v_pk_mul_f32 v[58:59], v[50:51], v[50:51]
	v_max_f32_e32 v40, v40, v40
	v_max_f32_e32 v41, v41, v41
	s_waitcnt lgkmcnt(0)
	v_mfma_f32_16x16x32_bf16 v[32:35], v[162:165], v[130:133], v[32:35]
	v_cvt_pk_bf16_f32 v48, v52, v53
	v_cvt_pk_bf16_f32 v49, v54, v55
	v_cvt_pk_bf16_f32 v50, v56, v57
	v_cvt_pk_bf16_f32 v51, v58, v59
	v_max_f32_e32 v40, 0, v40
	v_max_f32_e32 v41, 0, v41
	global_store_dwordx4 v[100:101], v[48:51], off offset:64
	v_max_f32_e32 v44, v44, v44
	v_max_f32_e32 v45, v45, v45
	v_pk_mul_f32 v[48:49], v[40:41], v[40:41]
	v_max_f32_e32 v41, v42, v42
	v_max_f32_e32 v40, v46, v46
	v_max_f32_e32 v42, 0, v41
	v_max_f32_e32 v41, v47, v47
	v_max_f32_e32 v43, v43, v43
	v_mfma_f32_16x16x32_bf16 v[36:39], v[74:77], v[130:133], v[36:39]
	v_max_f32_e32 v44, 0, v44
	v_max_f32_e32 v45, 0, v45
	v_max_f32_e32 v40, 0, v40
	v_max_f32_e32 v41, 0, v41
	v_max_f32_e32 v43, 0, v43
	v_pk_mul_f32 v[44:45], v[44:45], v[44:45]
	v_pk_mul_f32 v[46:47], v[40:41], v[40:41]
	v_pk_mul_f32 v[50:51], v[42:43], v[42:43]
	v_max_f32_e32 v32, v32, v32
	v_max_f32_e32 v33, v33, v33
	v_mfma_f32_16x16x32_bf16 v[24:27], v[146:149], v[134:137], v[24:27]
	v_cvt_pk_bf16_f32 v40, v44, v45
	v_cvt_pk_bf16_f32 v41, v46, v47
	v_cvt_pk_bf16_f32 v42, v48, v49
	v_cvt_pk_bf16_f32 v43, v50, v51
	v_max_f32_e32 v32, 0, v32
	v_max_f32_e32 v33, 0, v33
	global_store_dwordx4 v[100:101], v[40:43], off offset:128
	v_max_f32_e32 v36, v36, v36
	v_max_f32_e32 v37, v37, v37
	v_pk_mul_f32 v[40:41], v[32:33], v[32:33]
	v_max_f32_e32 v33, v34, v34
	v_max_f32_e32 v32, v38, v38
	v_max_f32_e32 v34, 0, v33
	v_max_f32_e32 v33, v39, v39
	v_max_f32_e32 v35, v35, v35
	v_mfma_f32_16x16x32_bf16 v[28:31], v[138:141], v[134:137], v[28:31]
	v_max_f32_e32 v36, 0, v36
	v_max_f32_e32 v37, 0, v37
	v_max_f32_e32 v32, 0, v32
	v_max_f32_e32 v33, 0, v33
	v_max_f32_e32 v35, 0, v35
	v_pk_mul_f32 v[36:37], v[36:37], v[36:37]
	v_pk_mul_f32 v[38:39], v[32:33], v[32:33]
	v_pk_mul_f32 v[42:43], v[34:35], v[34:35]
	v_max_f32_e32 v24, v24, v24
	v_max_f32_e32 v25, v25, v25
	v_mfma_f32_16x16x32_bf16 v[12:15], v[150:153], v[134:137], v[12:15]
	v_cvt_pk_bf16_f32 v32, v36, v37
	v_cvt_pk_bf16_f32 v33, v38, v39
	v_cvt_pk_bf16_f32 v34, v40, v41
	v_cvt_pk_bf16_f32 v35, v42, v43
	v_max_f32_e32 v24, 0, v24
	v_max_f32_e32 v25, 0, v25
	global_store_dwordx4 v[100:101], v[32:35], off offset:192
	v_max_f32_e32 v28, v28, v28
	v_max_f32_e32 v29, v29, v29
	v_pk_mul_f32 v[34:35], v[24:25], v[24:25]
	v_max_f32_e32 v25, v26, v26
	v_add_u32_e32 v32, s36, v84
	v_max_f32_e32 v24, v30, v30
	v_max_f32_e32 v26, 0, v25
	v_max_f32_e32 v25, v31, v31
	v_max_f32_e32 v27, v27, v27
	v_mfma_f32_16x16x32_bf16 v[16:19], v[94:97], v[134:137], v[16:19]
	v_mad_i64_i32 v[32:33], s[34:35], v32, s30, v[98:99]
	v_max_f32_e32 v28, 0, v28
	v_max_f32_e32 v29, 0, v29
	v_max_f32_e32 v24, 0, v24
	v_max_f32_e32 v25, 0, v25
	v_max_f32_e32 v27, 0, v27
	v_lshl_add_u64 v[32:33], v[32:33], 0, s[26:27]
	v_pk_mul_f32 v[28:29], v[28:29], v[28:29]
	v_pk_mul_f32 v[30:31], v[24:25], v[24:25]
	v_pk_mul_f32 v[36:37], v[26:27], v[26:27]
	v_max_f32_e32 v12, v12, v12
	v_max_f32_e32 v13, v13, v13
	v_mfma_f32_16x16x32_bf16 v[4:7], v[158:161], v[134:137], v[4:7]
	v_lshl_add_u64 v[32:33], v[32:33], 0, v[64:65]
	v_cvt_pk_bf16_f32 v24, v28, v29
	v_cvt_pk_bf16_f32 v25, v30, v31
	v_cvt_pk_bf16_f32 v26, v34, v35
	v_cvt_pk_bf16_f32 v27, v36, v37
	v_max_f32_e32 v12, 0, v12
	v_max_f32_e32 v13, 0, v13
	global_store_dwordx4 v[32:33], v[24:27], off
	v_max_f32_e32 v16, v16, v16
	v_max_f32_e32 v17, v17, v17
	v_pk_mul_f32 v[24:25], v[12:13], v[12:13]
	v_max_f32_e32 v13, v14, v14
	v_max_f32_e32 v12, v18, v18
	v_max_f32_e32 v14, 0, v13
	v_max_f32_e32 v13, v19, v19
	v_max_f32_e32 v15, v15, v15
	v_mfma_f32_16x16x32_bf16 v[8:11], v[154:157], v[134:137], v[8:11]
	v_max_f32_e32 v16, 0, v16
	v_max_f32_e32 v17, 0, v17
	v_max_f32_e32 v12, 0, v12
	v_max_f32_e32 v13, 0, v13
	v_max_f32_e32 v15, 0, v15
	v_pk_mul_f32 v[16:17], v[16:17], v[16:17]
	v_pk_mul_f32 v[18:19], v[12:13], v[12:13]
	v_pk_mul_f32 v[26:27], v[14:15], v[14:15]
	v_max_f32_e32 v4, v4, v4
	v_max_f32_e32 v5, v5, v5
	v_cvt_pk_bf16_f32 v12, v16, v17
	v_cvt_pk_bf16_f32 v13, v18, v19
	v_cvt_pk_bf16_f32 v14, v24, v25
	v_cvt_pk_bf16_f32 v15, v26, v27
	v_max_f32_e32 v4, 0, v4
	v_max_f32_e32 v5, 0, v5
	global_store_dwordx4 v[32:33], v[12:15], off offset:64
	v_mfma_f32_16x16x32_bf16 v[0:3], v[74:77], v[134:137], v[0:3]
	v_max_f32_e32 v8, v8, v8
	v_pk_mul_f32 v[12:13], v[4:5], v[4:5]
	v_max_f32_e32 v5, v6, v6
	v_mfma_f32_16x16x32_bf16 v[20:23], v[162:165], v[134:137], v[20:23]
	v_max_f32_e32 v9, v9, v9
	v_max_f32_e32 v4, v10, v10
	v_max_f32_e32 v6, 0, v5
	v_max_f32_e32 v5, v11, v11
	v_max_f32_e32 v7, v7, v7
	v_max_f32_e32 v8, 0, v8
	v_max_f32_e32 v9, 0, v9
	v_max_f32_e32 v4, 0, v4
	v_max_f32_e32 v5, 0, v5
	v_max_f32_e32 v7, 0, v7
	v_pk_mul_f32 v[8:9], v[8:9], v[8:9]
	v_pk_mul_f32 v[10:11], v[4:5], v[4:5]
	v_pk_mul_f32 v[14:15], v[6:7], v[6:7]
	v_cvt_pk_bf16_f32 v4, v8, v9
	v_cvt_pk_bf16_f32 v5, v10, v11
	v_cvt_pk_bf16_f32 v6, v12, v13
	v_cvt_pk_bf16_f32 v7, v14, v15
	global_store_dwordx4 v[32:33], v[4:7], off offset:128
	v_max_f32_e32 v0, v0, v0
	v_max_f32_e32 v1, v1, v1
	v_max_f32_e32 v4, v20, v20
	v_max_f32_e32 v5, v21, v21
	v_max_f32_e32 v2, v2, v2
	v_max_f32_e32 v6, v22, v22
	v_max_f32_e32 v3, v3, v3
	v_max_f32_e32 v7, v23, v23
	v_max_f32_e32 v0, 0, v0
	v_max_f32_e32 v4, 0, v4
	v_max_f32_e32 v1, 0, v1
	v_max_f32_e32 v5, 0, v5
	v_max_f32_e32 v2, 0, v2
	v_max_f32_e32 v6, 0, v6
	v_max_f32_e32 v3, 0, v3
	v_max_f32_e32 v7, 0, v7
	v_pk_mul_f32 v[0:1], v[0:1], v[0:1]
	v_pk_mul_f32 v[4:5], v[4:5], v[4:5]
	v_pk_mul_f32 v[2:3], v[2:3], v[2:3]
	v_pk_mul_f32 v[6:7], v[6:7], v[6:7]
	v_cvt_pk_bf16_f32 v0, v0, v1
	v_cvt_pk_bf16_f32 v1, v2, v3
	v_cvt_pk_bf16_f32 v2, v4, v5
	v_cvt_pk_bf16_f32 v3, v6, v7
	global_store_dwordx4 v[32:33], v[0:3], off offset:192
	s_cbranch_scc0 .LBB0_1005
